# v017 + static priority (no per-segment s_setprio flips) also in the split-K tail GEMM loop
# speedup vs baseline: 1.0066x; 1.0056x over previous
.LBB0_384:
	s_cmpk_lt_u32 s10, 0x100
	s_cbranch_scc0 .Lsp_tail384
	s_setprio 1
.Lsp_tail384:
	s_add_i32 s35, s14, 2
	s_add_u32 s36, s22, 0x100
	s_addc_u32 s37, s23, 0
	s_cmp_lg_u32 s34, s14
	s_cselect_b32 s14, s36, 0
	s_cselect_b32 s15, s37, 0
	s_add_u32 s40, s12, s14
	s_addc_u32 s41, s13, s15
	s_add_i32 s42, 0, 0x10000
	s_add_u32 s14, s0, s14
	v_add_u32_e32 v133, s42, v1
	s_addc_u32 s15, s1, s15
	s_add_i32 s43, 0, 0x14000
	ds_read_b128 v[144:147], v133
	ds_read_b128 v[148:151], v133 offset:1024
	ds_read_b128 v[152:155], v133 offset:2048
	ds_read_b128 v[168:171], v133 offset:3072
	v_add_u32_e32 v133, s43, v1
	ds_read_b128 v[172:175], v133
	ds_read_b128 v[176:179], v133 offset:1024
	ds_read_b128 v[180:183], v133 offset:2048
	ds_read_b128 v[184:187], v133 offset:3072
	v_lshl_add_u64 v[156:157], v[140:141], 0, s[22:23]
	s_add_i32 m0, s17, 0xc000
	ds_read_b128 v[188:191], v131
	ds_read_b128 v[192:195], v131 offset:1024
	ds_read_b128 v[196:199], v131 offset:2048
	ds_read_b128 v[200:203], v131 offset:3072
	ds_read_b128 v[204:207], v131 offset:4096
	ds_read_b128 v[216:219], v131 offset:5120
	ds_read_b128 v[220:223], v131 offset:6144
	ds_read_b128 v[224:227], v131 offset:7168
	global_load_lds_dwordx4 v[156:157], off
	v_lshl_add_u64 v[156:157], v[142:143], 0, s[22:23]
	s_add_i32 m0, s17, 0xe000
	s_nop 0
	global_load_lds_dwordx4 v[156:157], off
	s_waitcnt vmcnt(8)
	s_waitcnt lgkmcnt(0)
	s_barrier
	s_waitcnt lgkmcnt(0)
	v_mfma_f32_16x16x32_bf16 v[126:129], v[144:147], v[188:191], v[126:129]
	v_mfma_f32_16x16x32_bf16 v[126:129], v[148:151], v[192:195], v[126:129]
	v_mfma_f32_16x16x32_bf16 v[122:125], v[152:155], v[188:191], v[122:125]
	v_mfma_f32_16x16x32_bf16 v[122:125], v[168:171], v[192:195], v[122:125]
	v_mfma_f32_16x16x32_bf16 v[110:113], v[144:147], v[196:199], v[110:113]
	v_mfma_f32_16x16x32_bf16 v[110:113], v[148:151], v[200:203], v[110:113]
	v_mfma_f32_16x16x32_bf16 v[106:109], v[152:155], v[196:199], v[106:109]
	v_mfma_f32_16x16x32_bf16 v[106:109], v[168:171], v[200:203], v[106:109]
	v_mfma_f32_16x16x32_bf16 v[94:97], v[144:147], v[204:207], v[94:97]
	v_mfma_f32_16x16x32_bf16 v[94:97], v[148:151], v[216:219], v[94:97]
	v_mfma_f32_16x16x32_bf16 v[90:93], v[152:155], v[204:207], v[90:93]
	v_mfma_f32_16x16x32_bf16 v[90:93], v[168:171], v[216:219], v[90:93]
	v_mfma_f32_16x16x32_bf16 v[78:81], v[144:147], v[220:223], v[78:81]
	v_mfma_f32_16x16x32_bf16 v[78:81], v[148:151], v[224:227], v[78:81]
	v_mfma_f32_16x16x32_bf16 v[74:77], v[152:155], v[220:223], v[74:77]
	v_mfma_f32_16x16x32_bf16 v[74:77], v[168:171], v[224:227], v[74:77]
	v_mfma_f32_16x16x32_bf16 v[118:121], v[172:175], v[188:191], v[118:121]
	v_mfma_f32_16x16x32_bf16 v[118:121], v[176:179], v[192:195], v[118:121]
	v_mfma_f32_16x16x32_bf16 v[114:117], v[180:183], v[188:191], v[114:117]
	v_mfma_f32_16x16x32_bf16 v[114:117], v[184:187], v[192:195], v[114:117]
	v_mfma_f32_16x16x32_bf16 v[102:105], v[172:175], v[196:199], v[102:105]
	v_mfma_f32_16x16x32_bf16 v[102:105], v[176:179], v[200:203], v[102:105]
	v_mfma_f32_16x16x32_bf16 v[98:101], v[180:183], v[196:199], v[98:101]
	v_mfma_f32_16x16x32_bf16 v[98:101], v[184:187], v[200:203], v[98:101]
	v_mfma_f32_16x16x32_bf16 v[86:89], v[172:175], v[204:207], v[86:89]
	v_mfma_f32_16x16x32_bf16 v[86:89], v[176:179], v[216:219], v[86:89]
	v_mfma_f32_16x16x32_bf16 v[82:85], v[180:183], v[204:207], v[82:85]
	v_mfma_f32_16x16x32_bf16 v[82:85], v[184:187], v[216:219], v[82:85]
	v_mfma_f32_16x16x32_bf16 v[70:73], v[172:175], v[220:223], v[70:73]
	v_mfma_f32_16x16x32_bf16 v[70:73], v[176:179], v[224:227], v[70:73]
	v_mfma_f32_16x16x32_bf16 v[66:69], v[180:183], v[220:223], v[66:69]
	v_mfma_f32_16x16x32_bf16 v[66:69], v[184:187], v[224:227], v[66:69]
	s_barrier
	s_add_i32 s22, s42, s25
	v_lshl_add_u64 v[156:157], s[14:15], 0, v[158:159]
	s_mov_b32 m0, s22
	ds_read_b128 v[188:191], v131 offset:16384
	ds_read_b128 v[192:195], v131 offset:17408
	ds_read_b128 v[196:199], v131 offset:18432
	ds_read_b128 v[200:203], v131 offset:19456
	ds_read_b128 v[204:207], v131 offset:20480
	ds_read_b128 v[216:219], v131 offset:21504
	ds_read_b128 v[220:223], v131 offset:22528
	ds_read_b128 v[224:227], v131 offset:23552
	global_load_lds_dwordx4 v[156:157], off
	s_add_i32 m0, s22, 0x2000
	s_add_u32 s22, s14, 0x158000
	v_lshl_add_u64 v[228:229], s[14:15], 0, v[134:135]
	s_addc_u32 s23, s15, 0
	s_add_i32 s42, s43, s25
	global_load_lds_dwordx4 v[228:229], off
	v_lshl_add_u64 v[230:231], s[22:23], 0, v[158:159]
	s_mov_b32 m0, s42
	v_lshl_add_u64 v[232:233], s[40:41], 0, v[136:137]
	global_load_lds_dwordx4 v[230:231], off
	v_lshl_add_u64 v[230:231], s[22:23], 0, v[134:135]
	s_add_i32 m0, s42, 0x2000
	s_nop 0
	global_load_lds_dwordx4 v[230:231], off
	v_lshl_add_u64 v[230:231], s[40:41], 0, v[138:139]
	s_mov_b32 m0, s17
	s_nop 0
	global_load_lds_dwordx4 v[230:231], off
	s_mov_b32 m0, s26
	s_nop 0
	global_load_lds_dwordx4 v[232:233], off
	s_waitcnt vmcnt(8)
	s_waitcnt lgkmcnt(0)
	s_barrier
	s_waitcnt lgkmcnt(0)
	v_mfma_f32_16x16x32_bf16 v[62:65], v[144:147], v[188:191], v[62:65]
	v_mfma_f32_16x16x32_bf16 v[62:65], v[148:151], v[192:195], v[62:65]
	v_mfma_f32_16x16x32_bf16 v[58:61], v[152:155], v[188:191], v[58:61]
	v_mfma_f32_16x16x32_bf16 v[58:61], v[168:171], v[192:195], v[58:61]
	v_mfma_f32_16x16x32_bf16 v[46:49], v[144:147], v[196:199], v[46:49]
	v_mfma_f32_16x16x32_bf16 v[46:49], v[148:151], v[200:203], v[46:49]
	v_mfma_f32_16x16x32_bf16 v[42:45], v[152:155], v[196:199], v[42:45]
	v_mfma_f32_16x16x32_bf16 v[42:45], v[168:171], v[200:203], v[42:45]
	v_mfma_f32_16x16x32_bf16 v[30:33], v[144:147], v[204:207], v[30:33]
	v_mfma_f32_16x16x32_bf16 v[30:33], v[148:151], v[216:219], v[30:33]
	v_mfma_f32_16x16x32_bf16 v[26:29], v[152:155], v[204:207], v[26:29]
	v_mfma_f32_16x16x32_bf16 v[26:29], v[168:171], v[216:219], v[26:29]
	v_mfma_f32_16x16x32_bf16 v[14:17], v[144:147], v[220:223], v[14:17]
	v_mfma_f32_16x16x32_bf16 v[14:17], v[148:151], v[224:227], v[14:17]
	v_mfma_f32_16x16x32_bf16 v[10:13], v[152:155], v[220:223], v[10:13]
	v_mfma_f32_16x16x32_bf16 v[10:13], v[168:171], v[224:227], v[10:13]
	v_mfma_f32_16x16x32_bf16 v[54:57], v[172:175], v[188:191], v[54:57]
	v_mfma_f32_16x16x32_bf16 v[54:57], v[176:179], v[192:195], v[54:57]
	v_mfma_f32_16x16x32_bf16 v[50:53], v[180:183], v[188:191], v[50:53]
	v_mfma_f32_16x16x32_bf16 v[50:53], v[184:187], v[192:195], v[50:53]
	v_mfma_f32_16x16x32_bf16 v[38:41], v[172:175], v[196:199], v[38:41]
	v_mfma_f32_16x16x32_bf16 v[38:41], v[176:179], v[200:203], v[38:41]
	v_mfma_f32_16x16x32_bf16 v[34:37], v[180:183], v[196:199], v[34:37]
	v_mfma_f32_16x16x32_bf16 v[34:37], v[184:187], v[200:203], v[34:37]
	v_mfma_f32_16x16x32_bf16 v[22:25], v[172:175], v[204:207], v[22:25]
	v_mfma_f32_16x16x32_bf16 v[22:25], v[176:179], v[216:219], v[22:25]
	v_mfma_f32_16x16x32_bf16 v[18:21], v[180:183], v[204:207], v[18:21]
	v_mfma_f32_16x16x32_bf16 v[18:21], v[184:187], v[216:219], v[18:21]
	v_mfma_f32_16x16x32_bf16 v[6:9], v[172:175], v[220:223], v[6:9]
	v_mfma_f32_16x16x32_bf16 v[6:9], v[176:179], v[224:227], v[6:9]
	v_mfma_f32_16x16x32_bf16 v[2:5], v[180:183], v[220:223], v[2:5]
	v_mfma_f32_16x16x32_bf16 v[2:5], v[184:187], v[224:227], v[2:5]
	s_barrier
	s_add_i32 s42, 0, 0x18000
	v_add_u32_e32 v133, s42, v1
	s_add_i32 s43, 0, 0x1c000
	ds_read_b128 v[144:147], v133
	ds_read_b128 v[148:151], v133 offset:1024
	ds_read_b128 v[152:155], v133 offset:2048
	ds_read_b128 v[168:171], v133 offset:3072
	v_add_u32_e32 v133, s43, v1
	ds_read_b128 v[172:175], v133
	ds_read_b128 v[176:179], v133 offset:1024
	ds_read_b128 v[180:183], v133 offset:2048
	ds_read_b128 v[184:187], v133 offset:3072
	s_add_u32 s22, s40, 0x158000
	s_addc_u32 s23, s41, 0
	s_mov_b32 m0, s27
	v_lshl_add_u64 v[234:235], s[22:23], 0, v[138:139]
	ds_read_b128 v[188:191], v131 offset:32768
	ds_read_b128 v[192:195], v131 offset:33792
	ds_read_b128 v[196:199], v131 offset:34816
	ds_read_b128 v[200:203], v131 offset:35840
	ds_read_b128 v[204:207], v131 offset:36864
	ds_read_b128 v[216:219], v131 offset:37888
	ds_read_b128 v[220:223], v131 offset:38912
	ds_read_b128 v[224:227], v131 offset:39936
	global_load_lds_dwordx4 v[234:235], off
	v_lshl_add_u64 v[234:235], s[22:23], 0, v[136:137]
	s_mov_b32 m0, s28
	s_nop 0
	global_load_lds_dwordx4 v[234:235], off
	s_waitcnt vmcnt(8)
	s_waitcnt lgkmcnt(0)
	s_barrier
	s_waitcnt lgkmcnt(0)
	v_mfma_f32_16x16x32_bf16 v[126:129], v[144:147], v[188:191], v[126:129]
	v_mfma_f32_16x16x32_bf16 v[126:129], v[148:151], v[192:195], v[126:129]
	v_mfma_f32_16x16x32_bf16 v[122:125], v[152:155], v[188:191], v[122:125]
	v_mfma_f32_16x16x32_bf16 v[122:125], v[168:171], v[192:195], v[122:125]
	v_mfma_f32_16x16x32_bf16 v[110:113], v[144:147], v[196:199], v[110:113]
	v_mfma_f32_16x16x32_bf16 v[110:113], v[148:151], v[200:203], v[110:113]
	v_mfma_f32_16x16x32_bf16 v[106:109], v[152:155], v[196:199], v[106:109]
	v_mfma_f32_16x16x32_bf16 v[106:109], v[168:171], v[200:203], v[106:109]
	v_mfma_f32_16x16x32_bf16 v[94:97], v[144:147], v[204:207], v[94:97]
	v_mfma_f32_16x16x32_bf16 v[94:97], v[148:151], v[216:219], v[94:97]
	v_mfma_f32_16x16x32_bf16 v[90:93], v[152:155], v[204:207], v[90:93]
	v_mfma_f32_16x16x32_bf16 v[90:93], v[168:171], v[216:219], v[90:93]
	v_mfma_f32_16x16x32_bf16 v[78:81], v[144:147], v[220:223], v[78:81]
	v_mfma_f32_16x16x32_bf16 v[78:81], v[148:151], v[224:227], v[78:81]
	v_mfma_f32_16x16x32_bf16 v[74:77], v[152:155], v[220:223], v[74:77]
	v_mfma_f32_16x16x32_bf16 v[74:77], v[168:171], v[224:227], v[74:77]
	v_mfma_f32_16x16x32_bf16 v[118:121], v[172:175], v[188:191], v[118:121]
	v_mfma_f32_16x16x32_bf16 v[118:121], v[176:179], v[192:195], v[118:121]
	v_mfma_f32_16x16x32_bf16 v[114:117], v[180:183], v[188:191], v[114:117]
	v_mfma_f32_16x16x32_bf16 v[114:117], v[184:187], v[192:195], v[114:117]
	v_mfma_f32_16x16x32_bf16 v[102:105], v[172:175], v[196:199], v[102:105]
	v_mfma_f32_16x16x32_bf16 v[102:105], v[176:179], v[200:203], v[102:105]
	v_mfma_f32_16x16x32_bf16 v[98:101], v[180:183], v[196:199], v[98:101]
	v_mfma_f32_16x16x32_bf16 v[98:101], v[184:187], v[200:203], v[98:101]
	v_mfma_f32_16x16x32_bf16 v[86:89], v[172:175], v[204:207], v[86:89]
	v_mfma_f32_16x16x32_bf16 v[86:89], v[176:179], v[216:219], v[86:89]
	v_mfma_f32_16x16x32_bf16 v[82:85], v[180:183], v[204:207], v[82:85]
	v_mfma_f32_16x16x32_bf16 v[82:85], v[184:187], v[216:219], v[82:85]
	v_mfma_f32_16x16x32_bf16 v[70:73], v[172:175], v[220:223], v[70:73]
	v_mfma_f32_16x16x32_bf16 v[70:73], v[176:179], v[224:227], v[70:73]
	v_mfma_f32_16x16x32_bf16 v[66:69], v[180:183], v[220:223], v[66:69]
	v_mfma_f32_16x16x32_bf16 v[66:69], v[184:187], v[224:227], v[66:69]
	s_barrier
	s_add_i32 s22, s42, s25
	v_lshl_add_u64 v[156:157], v[156:157], 0, s[56:57]
	s_mov_b32 m0, s22
	ds_read_b128 v[188:191], v131 offset:49152
	ds_read_b128 v[192:195], v131 offset:50176
	ds_read_b128 v[196:199], v131 offset:51200
	ds_read_b128 v[200:203], v131 offset:52224
	ds_read_b128 v[204:207], v131 offset:53248
	ds_read_b128 v[216:219], v131 offset:54272
	ds_read_b128 v[220:223], v131 offset:55296
	ds_read_b128 v[224:227], v131 offset:56320
	global_load_lds_dwordx4 v[156:157], off
	s_add_i32 m0, s22, 0x2000
	s_add_u32 s14, s14, 0x158080
	v_lshl_add_u64 v[156:157], v[228:229], 0, s[56:57]
	s_addc_u32 s15, s15, 0
	s_add_i32 s22, s43, s25
	global_load_lds_dwordx4 v[156:157], off
	v_lshl_add_u64 v[156:157], s[14:15], 0, v[158:159]
	s_mov_b32 m0, s22
	s_nop 0
	global_load_lds_dwordx4 v[156:157], off
	v_lshl_add_u64 v[156:157], s[14:15], 0, v[134:135]
	s_add_i32 m0, s22, 0x2000
	s_nop 0
	global_load_lds_dwordx4 v[156:157], off
	v_lshl_add_u64 v[156:157], v[230:231], 0, s[56:57]
	s_mov_b32 m0, s29
	s_nop 0
	global_load_lds_dwordx4 v[156:157], off
	v_lshl_add_u64 v[156:157], v[232:233], 0, s[56:57]
	s_mov_b32 m0, s30
	s_nop 0
	global_load_lds_dwordx4 v[156:157], off
	s_waitcnt vmcnt(8)
	s_waitcnt lgkmcnt(0)
	s_barrier
	s_waitcnt lgkmcnt(0)
	v_mfma_f32_16x16x32_bf16 v[62:65], v[144:147], v[188:191], v[62:65]
	v_mfma_f32_16x16x32_bf16 v[62:65], v[148:151], v[192:195], v[62:65]
	v_mfma_f32_16x16x32_bf16 v[58:61], v[152:155], v[188:191], v[58:61]
	v_mfma_f32_16x16x32_bf16 v[58:61], v[168:171], v[192:195], v[58:61]
	v_mfma_f32_16x16x32_bf16 v[46:49], v[144:147], v[196:199], v[46:49]
	v_mfma_f32_16x16x32_bf16 v[46:49], v[148:151], v[200:203], v[46:49]
	v_mfma_f32_16x16x32_bf16 v[42:45], v[152:155], v[196:199], v[42:45]
	v_mfma_f32_16x16x32_bf16 v[42:45], v[168:171], v[200:203], v[42:45]
	v_mfma_f32_16x16x32_bf16 v[30:33], v[144:147], v[204:207], v[30:33]
	v_mfma_f32_16x16x32_bf16 v[30:33], v[148:151], v[216:219], v[30:33]
	v_mfma_f32_16x16x32_bf16 v[26:29], v[152:155], v[204:207], v[26:29]
	v_mfma_f32_16x16x32_bf16 v[26:29], v[168:171], v[216:219], v[26:29]
	v_mfma_f32_16x16x32_bf16 v[14:17], v[144:147], v[220:223], v[14:17]
	v_mfma_f32_16x16x32_bf16 v[14:17], v[148:151], v[224:227], v[14:17]
	v_mfma_f32_16x16x32_bf16 v[10:13], v[152:155], v[220:223], v[10:13]
	v_mfma_f32_16x16x32_bf16 v[10:13], v[168:171], v[224:227], v[10:13]
	v_mfma_f32_16x16x32_bf16 v[54:57], v[172:175], v[188:191], v[54:57]
	v_mfma_f32_16x16x32_bf16 v[54:57], v[176:179], v[192:195], v[54:57]
	v_mfma_f32_16x16x32_bf16 v[50:53], v[180:183], v[188:191], v[50:53]
	v_mfma_f32_16x16x32_bf16 v[50:53], v[184:187], v[192:195], v[50:53]
	v_mfma_f32_16x16x32_bf16 v[38:41], v[172:175], v[196:199], v[38:41]
	v_mfma_f32_16x16x32_bf16 v[38:41], v[176:179], v[200:203], v[38:41]
	v_mfma_f32_16x16x32_bf16 v[34:37], v[180:183], v[196:199], v[34:37]
	v_mfma_f32_16x16x32_bf16 v[34:37], v[184:187], v[200:203], v[34:37]
	v_mfma_f32_16x16x32_bf16 v[22:25], v[172:175], v[204:207], v[22:25]
	v_mfma_f32_16x16x32_bf16 v[22:25], v[176:179], v[216:219], v[22:25]
	v_mfma_f32_16x16x32_bf16 v[18:21], v[180:183], v[204:207], v[18:21]
	v_mfma_f32_16x16x32_bf16 v[18:21], v[184:187], v[216:219], v[18:21]
	v_mfma_f32_16x16x32_bf16 v[6:9], v[172:175], v[220:223], v[6:9]
	v_mfma_f32_16x16x32_bf16 v[6:9], v[176:179], v[224:227], v[6:9]
	v_mfma_f32_16x16x32_bf16 v[2:5], v[180:183], v[220:223], v[2:5]
	v_mfma_f32_16x16x32_bf16 v[2:5], v[184:187], v[224:227], v[2:5]
	s_barrier
	s_cmp_ge_i32 s35, s31
	s_mov_b64 s[22:23], s[36:37]
	s_mov_b32 s14, s35
	s_cbranch_scc0 .LBB0_384
	s_cmpk_lt_u32 s10, 0x100
	s_cbranch_scc0 .LBB0_387
